# v35 + MoE tile-loop lookup done lane-parallel (ballot) + kmean item issues all 16 row loads of an iteration before the first wait
# speedup vs baseline: 1.0049x; 1.0049x over previous
.LBB0_674:
	v_readlane_b32 s8, v237, 56
	v_readlane_b32 s10, v237, 58
	v_readlane_b32 s11, v237, 59
	s_add_i32 s17, s82, s10
	v_cmp_lt_i32_e64 s[10:11], s17, v129
	s_and_b64 s[0:1], s[10:11], exec
	s_cselect_b32 s83, s17, s82
	s_ashr_i32 s2, s83, 3
	s_cmp_gt_i32 s2, -1
	s_cselect_b64 s[0:1], -1, 0
	s_lshl_b32 s4, s2, 7
	v_readlane_b32 s9, v237, 57
	v_cmp_ge_i32_e64 s[8:9], s17, v129
	v_mbcnt_lo_u32_b32 v238, -1, 0
	v_mbcnt_hi_u32_b32 v238, -1, v238
	v_min_u32_e32 v239, 23, v238
	v_lshlrev_b32_e32 v239, 2, v239
	global_load_dword v240, v239, s[92:93]
	v_cmp_gt_u32_e32 vcc, 24, v238
	s_waitcnt vmcnt(0)
	s_nop 1
	v_cndmask_b32_e32 v240, 0, v240, vcc
	v_add_u32_e32 v241, 0x7f, v240
	v_ashrrev_i32_e32 v241, 7, v241
	v_mov_b32_e32 v242, v241
	v_mov_b32_e32 v243, v240
	s_nop 1
	v_add_u32_dpp v242, v242, v242 row_shr:1 row_mask:0xf bank_mask:0xf
	v_add_u32_dpp v243, v243, v243 row_shr:1 row_mask:0xf bank_mask:0xf
	s_nop 1
	v_add_u32_dpp v242, v242, v242 row_shr:2 row_mask:0xf bank_mask:0xf
	v_add_u32_dpp v243, v243, v243 row_shr:2 row_mask:0xf bank_mask:0xf
	s_nop 1
	v_add_u32_dpp v242, v242, v242 row_shr:4 row_mask:0xf bank_mask:0xf
	v_add_u32_dpp v243, v243, v243 row_shr:4 row_mask:0xf bank_mask:0xf
	s_nop 1
	v_add_u32_dpp v242, v242, v242 row_shr:8 row_mask:0xf bank_mask:0xf
	v_add_u32_dpp v243, v243, v243 row_shr:8 row_mask:0xf bank_mask:0xf
	s_nop 1
	v_readlane_b32 s98, v242, 15
	v_readlane_b32 s99, v243, 15
	v_cmp_lt_u32_e32 vcc, 15, v238
	s_nop 1
	v_mov_b32_e32 v244, s98
	v_mov_b32_e32 v245, s99
	v_cndmask_b32_e32 v244, 0, v244, vcc
	v_cndmask_b32_e32 v245, 0, v245, vcc
	v_add_u32_e32 v242, v242, v244
	v_add_u32_e32 v243, v243, v245
	v_sub_u32_e32 v246, v242, v241
	v_sub_u32_e32 v247, v243, v240
	v_cmp_le_i32_e64 s[98:99], v246, s2
	v_cmp_gt_i32_e64 s[100:101], v242, s2
	s_nop 1
	s_and_b64 s[98:99], s[98:99], s[100:101]
	s_ff1_i32_b64 s98, s[98:99]
	s_max_i32 s98, s98, 0
	s_nop 3
	v_readlane_b32 s99, v246, s98
	v_readlane_b32 s100, v240, s98
	v_readlane_b32 s101, v247, s98
	s_sub_i32 s99, s2, s99
	s_lshl_b32 s99, s99, 7
	v_mov_b32_e32 v134, s98
	v_mov_b32_e32 v150, s99
	v_mov_b32_e32 v151, s100
	v_mov_b32_e32 v152, s101
	v_readlane_b32 s12, v237, 25
	v_readlane_b32 s13, v237, 26
	v_readlane_b32 s0, v236, 8
	v_readlane_b32 s1, v236, 9
	v_readlane_b32 s0, v236, 6
	v_readlane_b32 s1, v236, 7
	v_readlane_b32 s0, v236, 2
	v_readlane_b32 s1, v236, 3
	v_readlane_b32 s0, v236, 4
	v_readlane_b32 s1, v236, 5
	v_readlane_b32 s0, v237, 62
	v_readlane_b32 s1, v237, 63
	v_readlane_b32 s0, v236, 0
	v_readlane_b32 s1, v236, 1
	v_readlane_b32 s0, v237, 60
	v_readlane_b32 s1, v237, 61
	v_readlane_b32 s0, v236, 10
	v_readlane_b32 s1, v236, 11

.LBB0_814:
	v_readlane_b32 s8, v237, 56
	v_readlane_b32 s10, v237, 58
	v_readlane_b32 s11, v237, 59
	s_add_i32 s17, s16, s10
	v_cmp_lt_i32_e64 s[10:11], s17, v129
	s_and_b64 s[0:1], s[10:11], exec
	s_cselect_b32 s33, s17, s16
	s_ashr_i32 s2, s33, 3
	s_cmp_gt_i32 s2, -1
	s_cselect_b64 s[0:1], -1, 0
	s_lshl_b32 s12, s2, 7
	v_readlane_b32 s9, v237, 57
	v_cmp_ge_i32_e64 s[8:9], s17, v129
	v_mbcnt_lo_u32_b32 v238, -1, 0
	v_mbcnt_hi_u32_b32 v238, -1, v238
	v_min_u32_e32 v239, 23, v238
	v_lshlrev_b32_e32 v239, 2, v239
	global_load_dword v240, v239, s[92:93]
	v_cmp_gt_u32_e32 vcc, 24, v238
	s_waitcnt vmcnt(0)
	s_nop 1
	v_cndmask_b32_e32 v240, 0, v240, vcc
	v_add_u32_e32 v241, 0x7f, v240
	v_ashrrev_i32_e32 v241, 7, v241
	v_mov_b32_e32 v242, v241
	v_mov_b32_e32 v243, v240
	s_nop 1
	v_add_u32_dpp v242, v242, v242 row_shr:1 row_mask:0xf bank_mask:0xf
	v_add_u32_dpp v243, v243, v243 row_shr:1 row_mask:0xf bank_mask:0xf
	s_nop 1
	v_add_u32_dpp v242, v242, v242 row_shr:2 row_mask:0xf bank_mask:0xf
	v_add_u32_dpp v243, v243, v243 row_shr:2 row_mask:0xf bank_mask:0xf
	s_nop 1
	v_add_u32_dpp v242, v242, v242 row_shr:4 row_mask:0xf bank_mask:0xf
	v_add_u32_dpp v243, v243, v243 row_shr:4 row_mask:0xf bank_mask:0xf
	s_nop 1
	v_add_u32_dpp v242, v242, v242 row_shr:8 row_mask:0xf bank_mask:0xf
	v_add_u32_dpp v243, v243, v243 row_shr:8 row_mask:0xf bank_mask:0xf
	s_nop 1
	v_readlane_b32 s98, v242, 15
	v_readlane_b32 s99, v243, 15
	v_cmp_lt_u32_e32 vcc, 15, v238
	s_nop 1
	v_mov_b32_e32 v244, s98
	v_mov_b32_e32 v245, s99
	v_cndmask_b32_e32 v244, 0, v244, vcc
	v_cndmask_b32_e32 v245, 0, v245, vcc
	v_add_u32_e32 v242, v242, v244
	v_add_u32_e32 v243, v243, v245
	v_sub_u32_e32 v246, v242, v241
	v_sub_u32_e32 v247, v243, v240
	v_cmp_le_i32_e64 s[98:99], v246, s2
	v_cmp_gt_i32_e64 s[100:101], v242, s2
	s_nop 1
	s_and_b64 s[98:99], s[98:99], s[100:101]
	s_ff1_i32_b64 s98, s[98:99]
	s_max_i32 s98, s98, 0
	s_nop 3
	v_readlane_b32 s99, v246, s98
	v_readlane_b32 s100, v240, s98
	v_readlane_b32 s101, v247, s98
	s_sub_i32 s99, s2, s99
	s_lshl_b32 s99, s99, 7
	v_mov_b32_e32 v146, s98
	v_mov_b32_e32 v145, s99
	v_mov_b32_e32 v147, s100
	v_mov_b32_e32 v64, s101
	v_readlane_b32 s18, v237, 27
	v_readlane_b32 s19, v237, 28
	v_readlane_b32 s0, v236, 6
	v_readlane_b32 s1, v236, 7
	v_readlane_b32 s0, v236, 2
	v_readlane_b32 s1, v236, 3
	v_readlane_b32 s0, v236, 4
	v_readlane_b32 s1, v236, 5
	v_readlane_b32 s0, v237, 62
	v_readlane_b32 s1, v237, 63
	v_readlane_b32 s0, v236, 0
	v_readlane_b32 s1, v236, 1
	v_readlane_b32 s0, v237, 60
	v_readlane_b32 s1, v237, 61
	v_readlane_b32 s0, v236, 10
	v_readlane_b32 s1, v236, 11
